# gemm_in 8-phase K-loop: LDS-DMA pairs use the scalar-base form with M0 values precomputed in SGPRs, removing 2 v_lshl_add_u64 + 2 v_readfirstlane per phase from the loop
# speedup vs baseline: 1.0152x; 1.0035x over previous
.LBB0_361:
	v_and_b32_e32 v2, 15, v1
	v_and_b32_e32 v3, 48, v1
	v_lshlrev_b32_e32 v2, 6, v2
	v_lshlrev_b32_e32 v1, 2, v1
	v_or_b32_e32 v4, v2, v3
	v_and_b32_e32 v1, 32, v1
	s_lshl_b32 s38, s38, 13
	v_bitop3_b32 v4, v4, s38, v1 bitop3:0xde
	s_lshl_b32 s38, s47, 6
	v_bitop3_b32 v2, v2, v1, v3 bitop3:0x36
	s_and_b32 s38, s38, 0x3000
	v_or_b32_e32 v137, s38, v2
	s_add_u32 s38, s0, 0x80
	s_addc_u32 s39, s1, 0
	v_add_u32_e32 v138, s93, v0
	v_lshl_add_u64 v[2:3], s[38:39], 0, v[192:193]
	v_readfirstlane_b32 s38, v138
	v_add_u32_e32 v139, 0x2000, v138
	s_mov_b32 m0, s38
	v_readfirstlane_b32 s38, v139
	s_waitcnt vmcnt(4)
	s_barrier
	global_load_lds_dwordx4 v[2:3], off
	s_mov_b32 m0, s38
	s_add_u32 s38, s2, 0x80
	v_lshl_add_u64 v[2:3], v[2:3], 0, s[4:5]
	s_addc_u32 s39, s3, 0
	v_add_u32_e32 v140, 0x8000, v131
	global_load_lds_dwordx4 v[2:3], off
	v_lshl_add_u64 v[2:3], s[38:39], 0, v[192:193]
	v_readfirstlane_b32 s38, v140
	v_add_u32_e32 v141, 0xa000, v131
	s_mov_b32 m0, s38
	v_readfirstlane_b32 s38, v141
	global_load_lds_dwordx4 v[2:3], off
	s_mov_b32 m0, s38
	s_add_u32 s38, s12, 0x80
	v_lshl_add_u64 v[2:3], v[2:3], 0, s[4:5]
	s_addc_u32 s39, s13, 0
	v_add_u32_e32 v142, s89, v0
	global_load_lds_dwordx4 v[2:3], off
	v_lshl_add_u64 v[2:3], s[38:39], 0, v[192:193]
	v_readfirstlane_b32 s38, v142
	v_add_u32_e32 v143, 0x2000, v142
	s_mov_b32 m0, s38
	v_readfirstlane_b32 s38, v143
	global_load_lds_dwordx4 v[2:3], off
	v_lshl_add_u64 v[0:1], v[2:3], 0, s[4:5]
	s_mov_b32 m0, s38
	s_mov_b32 s48, -2
	global_load_lds_dwordx4 v[0:1], off
	s_waitcnt vmcnt(6)
	v_mov_b32_e32 v0, 0
	s_mov_b64 s[38:39], 0
	v_add_u32_e32 v128, 0, v4
	v_mov_b32_e32 v1, v0
	v_mov_b32_e32 v2, v0
	v_mov_b32_e32 v3, v0
	v_mov_b32_e32 v4, v0
	v_mov_b32_e32 v5, v0
	v_mov_b32_e32 v6, v0
	v_mov_b32_e32 v7, v0
	v_mov_b32_e32 v8, v0
	v_mov_b32_e32 v9, v0
	v_mov_b32_e32 v10, v0
	v_mov_b32_e32 v11, v0
	v_mov_b32_e32 v12, v0
	v_mov_b32_e32 v13, v0
	v_mov_b32_e32 v14, v0
	v_mov_b32_e32 v15, v0
	v_mov_b32_e32 v16, v0
	v_mov_b32_e32 v17, v0
	v_mov_b32_e32 v18, v0
	v_mov_b32_e32 v19, v0
	v_mov_b32_e32 v20, v0
	v_mov_b32_e32 v21, v0
	v_mov_b32_e32 v22, v0
	v_mov_b32_e32 v23, v0
	v_mov_b32_e32 v24, v0
	v_mov_b32_e32 v25, v0
	v_mov_b32_e32 v26, v0
	v_mov_b32_e32 v27, v0
	v_mov_b32_e32 v28, v0
	v_mov_b32_e32 v29, v0
	v_mov_b32_e32 v30, v0
	v_mov_b32_e32 v31, v0
	v_mov_b32_e32 v32, v0
	v_mov_b32_e32 v33, v0
	v_mov_b32_e32 v34, v0
	v_mov_b32_e32 v35, v0
	v_mov_b32_e32 v36, v0
	v_mov_b32_e32 v37, v0
	v_mov_b32_e32 v38, v0
	v_mov_b32_e32 v39, v0
	v_mov_b32_e32 v40, v0
	v_mov_b32_e32 v41, v0
	v_mov_b32_e32 v42, v0
	v_mov_b32_e32 v43, v0
	v_mov_b32_e32 v44, v0
	v_mov_b32_e32 v45, v0
	v_mov_b32_e32 v46, v0
	v_mov_b32_e32 v47, v0
	v_mov_b32_e32 v48, v0
	v_mov_b32_e32 v49, v0
	v_mov_b32_e32 v50, v0
	v_mov_b32_e32 v51, v0
	v_mov_b32_e32 v52, v0
	v_mov_b32_e32 v53, v0
	v_mov_b32_e32 v54, v0
	v_mov_b32_e32 v55, v0
	v_mov_b32_e32 v56, v0
	v_mov_b32_e32 v57, v0
	v_mov_b32_e32 v58, v0
	v_mov_b32_e32 v59, v0
	v_mov_b32_e32 v60, v0
	v_mov_b32_e32 v61, v0
	v_mov_b32_e32 v62, v0
	v_mov_b32_e32 v63, v0
	v_mov_b32_e32 v64, v0
	v_mov_b32_e32 v65, v0
	v_mov_b32_e32 v66, v0
	v_mov_b32_e32 v67, v0
	v_mov_b32_e32 v68, v0
	v_mov_b32_e32 v69, v0
	v_mov_b32_e32 v70, v0
	v_mov_b32_e32 v71, v0
	v_mov_b32_e32 v72, v0
	v_mov_b32_e32 v73, v0
	v_mov_b32_e32 v74, v0
	v_mov_b32_e32 v75, v0
	v_mov_b32_e32 v76, v0
	v_mov_b32_e32 v77, v0
	v_mov_b32_e32 v78, v0
	v_mov_b32_e32 v79, v0
	v_mov_b32_e32 v80, v0
	v_mov_b32_e32 v81, v0
	v_mov_b32_e32 v82, v0
	v_mov_b32_e32 v83, v0
	v_mov_b32_e32 v84, v0
	v_mov_b32_e32 v85, v0
	v_mov_b32_e32 v86, v0
	v_mov_b32_e32 v87, v0
	v_mov_b32_e32 v88, v0
	v_mov_b32_e32 v89, v0
	v_mov_b32_e32 v90, v0
	v_mov_b32_e32 v91, v0
	v_mov_b32_e32 v92, v0
	v_mov_b32_e32 v93, v0
	v_mov_b32_e32 v94, v0
	v_mov_b32_e32 v95, v0
	v_mov_b32_e32 v96, v0
	v_mov_b32_e32 v97, v0
	v_mov_b32_e32 v98, v0
	v_mov_b32_e32 v99, v0
	v_mov_b32_e32 v100, v0
	v_mov_b32_e32 v101, v0
	v_mov_b32_e32 v102, v0
	v_mov_b32_e32 v103, v0
	v_mov_b32_e32 v104, v0
	v_mov_b32_e32 v105, v0
	v_mov_b32_e32 v106, v0
	v_mov_b32_e32 v107, v0
	v_mov_b32_e32 v108, v0
	v_mov_b32_e32 v109, v0
	v_mov_b32_e32 v110, v0
	v_mov_b32_e32 v111, v0
	v_mov_b32_e32 v112, v0
	v_mov_b32_e32 v113, v0
	v_mov_b32_e32 v114, v0
	v_mov_b32_e32 v115, v0
	v_mov_b32_e32 v116, v0
	v_mov_b32_e32 v117, v0
	v_mov_b32_e32 v118, v0
	v_mov_b32_e32 v119, v0
	v_mov_b32_e32 v120, v0
	v_mov_b32_e32 v121, v0
	v_mov_b32_e32 v122, v0
	v_mov_b32_e32 v123, v0
	v_mov_b32_e32 v124, v0
	v_mov_b32_e32 v125, v0
	v_mov_b32_e32 v126, v0
	v_mov_b32_e32 v127, v0
	v_readfirstlane_b32 s14, v131
	s_add_i32 s14, s14, 0xc000
	v_readfirstlane_b32 s15, v131
	s_add_i32 s15, s15, 0xe000
	v_readfirstlane_b32 s16, v129
	v_readfirstlane_b32 s17, v130
	v_readfirstlane_b32 s18, v131
	v_readfirstlane_b32 s19, v132
	v_readfirstlane_b32 s20, v133
	v_readfirstlane_b32 s21, v134
	v_readfirstlane_b32 s22, v135
	v_readfirstlane_b32 s23, v136
	v_readfirstlane_b32 s24, v138
	v_readfirstlane_b32 s25, v139
	v_readfirstlane_b32 s26, v140
	v_readfirstlane_b32 s27, v141
	v_readfirstlane_b32 s28, v142
	v_readfirstlane_b32 s29, v143
	s_barrier
.LBB0_362:
	v_add_u32_e32 v144, s77, v137
	ds_read_b128 v[146:149], v144
	ds_read_b128 v[150:153], v144 offset:1024
	ds_read_b128 v[154:157], v144 offset:2048
	ds_read_b128 v[158:161], v144 offset:3072
	s_add_u32 s49, s36, s38
	s_addc_u32 s52, s37, s39
	s_add_u32 s50, s49, 0x80
	s_addc_u32 s51, s52, 0
	v_add_u32_e32 v144, 0xc000, v131
	v_add_u32_e32 v145, 0xe000, v131
	s_mov_b32 m0, s14
	ds_read_b128 v[162:165], v128
	ds_read_b128 v[166:169], v128 offset:1024
	ds_read_b128 v[170:173], v128 offset:2048
	ds_read_b128 v[174:177], v128 offset:3072
	ds_read_b128 v[178:181], v128 offset:4096
	ds_read_b128 v[182:185], v128 offset:5120
	ds_read_b128 v[186:189], v128 offset:6144
	ds_read_b128 v[196:199], v128 offset:7168
	global_load_lds_dwordx4 v192, s[50:51]
	s_add_u32 s30, s50, s4
	s_addc_u32 s31, s51, s5
	s_mov_b32 m0, s15
	s_nop 0
	global_load_lds_dwordx4 v192, s[30:31]
	s_waitcnt lgkmcnt(8)
	s_barrier
	s_waitcnt lgkmcnt(0)
	s_waitcnt lgkmcnt(0)
	v_mfma_f32_16x16x32_bf16 v[124:127], v[162:165], v[146:149], v[124:127]
	v_mfma_f32_16x16x32_bf16 v[120:123], v[162:165], v[154:157], v[120:123]
	v_mfma_f32_16x16x32_bf16 v[116:119], v[170:173], v[146:149], v[116:119]
	v_mfma_f32_16x16x32_bf16 v[112:115], v[170:173], v[154:157], v[112:115]
	v_mfma_f32_16x16x32_bf16 v[108:111], v[178:181], v[146:149], v[108:111]
	v_mfma_f32_16x16x32_bf16 v[104:107], v[178:181], v[154:157], v[104:107]
	v_mfma_f32_16x16x32_bf16 v[100:103], v[186:189], v[146:149], v[100:103]
	v_mfma_f32_16x16x32_bf16 v[96:99], v[186:189], v[154:157], v[96:99]
	v_mfma_f32_16x16x32_bf16 v[124:127], v[166:169], v[150:153], v[124:127]
	v_mfma_f32_16x16x32_bf16 v[120:123], v[166:169], v[158:161], v[120:123]
	v_mfma_f32_16x16x32_bf16 v[116:119], v[174:177], v[150:153], v[116:119]
	v_mfma_f32_16x16x32_bf16 v[112:115], v[174:177], v[158:161], v[112:115]
	v_mfma_f32_16x16x32_bf16 v[108:111], v[182:185], v[150:153], v[108:111]
	v_mfma_f32_16x16x32_bf16 v[104:107], v[182:185], v[158:161], v[104:107]
	v_mfma_f32_16x16x32_bf16 v[100:103], v[196:199], v[150:153], v[100:103]
	v_mfma_f32_16x16x32_bf16 v[96:99], v[196:199], v[158:161], v[96:99]
	s_barrier
	s_add_u32 s53, s0, s38
	s_addc_u32 s54, s1, s39
	s_add_u32 s50, s53, 0x100
	v_add_u32_e32 v190, s33, v137
	s_addc_u32 s51, s54, 0
	ds_read_b128 v[200:203], v190
	ds_read_b128 v[204:207], v190 offset:1024
	ds_read_b128 v[208:211], v190 offset:2048
	ds_read_b128 v[212:215], v190 offset:3072
	s_mov_b32 m0, s16
	s_nop 0
	global_load_lds_dwordx4 v192, s[50:51]
	s_add_u32 s30, s50, s4
	s_addc_u32 s31, s51, s5
	s_mov_b32 m0, s17
	s_nop 0
	global_load_lds_dwordx4 v192, s[30:31]
	s_barrier
	s_waitcnt lgkmcnt(0)
	s_waitcnt lgkmcnt(0)
	v_mfma_f32_16x16x32_bf16 v[92:95], v[162:165], v[200:203], v[92:95]
	v_mfma_f32_16x16x32_bf16 v[88:91], v[162:165], v[208:211], v[88:91]
	v_mfma_f32_16x16x32_bf16 v[84:87], v[170:173], v[200:203], v[84:87]
	v_mfma_f32_16x16x32_bf16 v[80:83], v[170:173], v[208:211], v[80:83]
	v_mfma_f32_16x16x32_bf16 v[76:79], v[178:181], v[200:203], v[76:79]
	v_mfma_f32_16x16x32_bf16 v[72:75], v[178:181], v[208:211], v[72:75]
	v_mfma_f32_16x16x32_bf16 v[68:71], v[186:189], v[200:203], v[68:71]
	v_mfma_f32_16x16x32_bf16 v[64:67], v[186:189], v[208:211], v[64:67]
	v_mfma_f32_16x16x32_bf16 v[92:95], v[166:169], v[204:207], v[92:95]
	v_mfma_f32_16x16x32_bf16 v[88:91], v[166:169], v[212:215], v[88:91]
	v_mfma_f32_16x16x32_bf16 v[84:87], v[174:177], v[204:207], v[84:87]
	v_mfma_f32_16x16x32_bf16 v[80:83], v[174:177], v[212:215], v[80:83]
	v_mfma_f32_16x16x32_bf16 v[76:79], v[182:185], v[204:207], v[76:79]
	v_mfma_f32_16x16x32_bf16 v[72:75], v[182:185], v[212:215], v[72:75]
	v_mfma_f32_16x16x32_bf16 v[68:71], v[196:199], v[204:207], v[68:71]
	v_mfma_f32_16x16x32_bf16 v[64:67], v[196:199], v[212:215], v[64:67]
	s_add_u32 s55, s2, s38
	s_addc_u32 s72, s3, s39
	s_add_u32 s50, s55, 0x100
	s_addc_u32 s51, s72, 0
	s_mov_b32 m0, s18
	s_barrier
	ds_read_b128 v[162:165], v128 offset:16384
	ds_read_b128 v[166:169], v128 offset:17408
	ds_read_b128 v[170:173], v128 offset:18432
	ds_read_b128 v[174:177], v128 offset:19456
	ds_read_b128 v[178:181], v128 offset:20480
	ds_read_b128 v[182:185], v128 offset:21504
	ds_read_b128 v[186:189], v128 offset:22528
	ds_read_b128 v[196:199], v128 offset:23552
	global_load_lds_dwordx4 v192, s[50:51]
	s_add_u32 s30, s50, s4
	s_addc_u32 s31, s51, s5
	s_mov_b32 m0, s19
	s_nop 0
	global_load_lds_dwordx4 v192, s[30:31]
	s_barrier
	s_waitcnt lgkmcnt(0)
	s_waitcnt lgkmcnt(0)
	v_mfma_f32_16x16x32_bf16 v[60:63], v[162:165], v[146:149], v[60:63]
	v_mfma_f32_16x16x32_bf16 v[56:59], v[162:165], v[154:157], v[56:59]
	v_mfma_f32_16x16x32_bf16 v[52:55], v[170:173], v[146:149], v[52:55]
	v_mfma_f32_16x16x32_bf16 v[48:51], v[170:173], v[154:157], v[48:51]
	v_mfma_f32_16x16x32_bf16 v[44:47], v[178:181], v[146:149], v[44:47]
	v_mfma_f32_16x16x32_bf16 v[40:43], v[178:181], v[154:157], v[40:43]
	v_mfma_f32_16x16x32_bf16 v[36:39], v[186:189], v[146:149], v[36:39]
	v_mfma_f32_16x16x32_bf16 v[32:35], v[186:189], v[154:157], v[32:35]
	v_mfma_f32_16x16x32_bf16 v[60:63], v[166:169], v[150:153], v[60:63]
	v_mfma_f32_16x16x32_bf16 v[56:59], v[166:169], v[158:161], v[56:59]
	v_mfma_f32_16x16x32_bf16 v[52:55], v[174:177], v[150:153], v[52:55]
	v_mfma_f32_16x16x32_bf16 v[48:51], v[174:177], v[158:161], v[48:51]
	v_mfma_f32_16x16x32_bf16 v[44:47], v[182:185], v[150:153], v[44:47]
	v_mfma_f32_16x16x32_bf16 v[40:43], v[182:185], v[158:161], v[40:43]
	v_mfma_f32_16x16x32_bf16 v[36:39], v[196:199], v[150:153], v[36:39]
	v_mfma_f32_16x16x32_bf16 v[32:35], v[196:199], v[158:161], v[32:35]
	s_barrier
	s_add_u32 s73, s12, s38
	s_addc_u32 s74, s13, s39
	s_add_u32 s50, s73, 0x100
	s_addc_u32 s51, s74, 0
	s_mov_b32 m0, s20
	s_nop 0
	global_load_lds_dwordx4 v192, s[50:51]
	s_add_u32 s30, s50, s4
	s_addc_u32 s31, s51, s5
	s_mov_b32 m0, s21
	s_nop 0
	global_load_lds_dwordx4 v192, s[30:31]
	s_waitcnt vmcnt(6)
	s_barrier
	v_mfma_f32_16x16x32_bf16 v[28:31], v[162:165], v[200:203], v[28:31]
	v_mfma_f32_16x16x32_bf16 v[24:27], v[162:165], v[208:211], v[24:27]
	v_mfma_f32_16x16x32_bf16 v[20:23], v[170:173], v[200:203], v[20:23]
	v_mfma_f32_16x16x32_bf16 v[16:19], v[170:173], v[208:211], v[16:19]
	v_mfma_f32_16x16x32_bf16 v[12:15], v[178:181], v[200:203], v[12:15]
	v_mfma_f32_16x16x32_bf16 v[8:11], v[178:181], v[208:211], v[8:11]
	v_mfma_f32_16x16x32_bf16 v[4:7], v[186:189], v[200:203], v[4:7]
	v_mfma_f32_16x16x32_bf16 v[0:3], v[186:189], v[208:211], v[0:3]
	v_mfma_f32_16x16x32_bf16 v[28:31], v[166:169], v[204:207], v[28:31]
	v_mfma_f32_16x16x32_bf16 v[24:27], v[166:169], v[212:215], v[24:27]
	v_mfma_f32_16x16x32_bf16 v[20:23], v[174:177], v[204:207], v[20:23]
	v_mfma_f32_16x16x32_bf16 v[16:19], v[174:177], v[212:215], v[16:19]
	v_mfma_f32_16x16x32_bf16 v[12:15], v[182:185], v[204:207], v[12:15]
	v_mfma_f32_16x16x32_bf16 v[8:11], v[182:185], v[212:215], v[8:11]
	v_mfma_f32_16x16x32_bf16 v[4:7], v[196:199], v[204:207], v[4:7]
	v_mfma_f32_16x16x32_bf16 v[0:3], v[196:199], v[212:215], v[0:3]
	v_add_u32_e32 v158, s93, v137
	s_barrier
	ds_read_b128 v[146:149], v158
	ds_read_b128 v[150:153], v158 offset:1024
	ds_read_b128 v[154:157], v158 offset:2048
	ds_read_b128 v[158:161], v158 offset:3072
	s_add_u32 s50, s49, 0x100
	s_addc_u32 s51, s52, 0
	s_mov_b32 m0, s22
	ds_read_b128 v[162:165], v128 offset:32768
	ds_read_b128 v[166:169], v128 offset:33792
	ds_read_b128 v[170:173], v128 offset:34816
	ds_read_b128 v[174:177], v128 offset:35840
	ds_read_b128 v[178:181], v128 offset:36864
	ds_read_b128 v[182:185], v128 offset:37888
	ds_read_b128 v[186:189], v128 offset:38912
	ds_read_b128 v[196:199], v128 offset:39936
	global_load_lds_dwordx4 v192, s[50:51]
	s_add_u32 s30, s50, s4
	s_addc_u32 s31, s51, s5
	s_mov_b32 m0, s23
	s_nop 0
	global_load_lds_dwordx4 v192, s[30:31]
	s_waitcnt lgkmcnt(8)
	s_barrier
	s_waitcnt lgkmcnt(0)
	s_waitcnt lgkmcnt(0)
	v_mfma_f32_16x16x32_bf16 v[124:127], v[162:165], v[146:149], v[124:127]
	v_mfma_f32_16x16x32_bf16 v[120:123], v[162:165], v[154:157], v[120:123]
	v_mfma_f32_16x16x32_bf16 v[116:119], v[170:173], v[146:149], v[116:119]
	v_mfma_f32_16x16x32_bf16 v[112:115], v[170:173], v[154:157], v[112:115]
	v_mfma_f32_16x16x32_bf16 v[108:111], v[178:181], v[146:149], v[108:111]
	v_mfma_f32_16x16x32_bf16 v[104:107], v[178:181], v[154:157], v[104:107]
	v_mfma_f32_16x16x32_bf16 v[100:103], v[186:189], v[146:149], v[100:103]
	v_mfma_f32_16x16x32_bf16 v[96:99], v[186:189], v[154:157], v[96:99]
	v_mfma_f32_16x16x32_bf16 v[124:127], v[166:169], v[150:153], v[124:127]
	v_mfma_f32_16x16x32_bf16 v[120:123], v[166:169], v[158:161], v[120:123]
	v_mfma_f32_16x16x32_bf16 v[116:119], v[174:177], v[150:153], v[116:119]
	v_mfma_f32_16x16x32_bf16 v[112:115], v[174:177], v[158:161], v[112:115]
	v_mfma_f32_16x16x32_bf16 v[108:111], v[182:185], v[150:153], v[108:111]
	v_mfma_f32_16x16x32_bf16 v[104:107], v[182:185], v[158:161], v[104:107]
	v_mfma_f32_16x16x32_bf16 v[100:103], v[196:199], v[150:153], v[100:103]
	v_mfma_f32_16x16x32_bf16 v[96:99], v[196:199], v[158:161], v[96:99]
	s_barrier
	s_add_u32 s50, s53, 0x180
	v_add_u32_e32 v190, s89, v137
	s_addc_u32 s51, s54, 0
	ds_read_b128 v[200:203], v190
	ds_read_b128 v[204:207], v190 offset:1024
	ds_read_b128 v[208:211], v190 offset:2048
	ds_read_b128 v[212:215], v190 offset:3072
	s_mov_b32 m0, s24
	s_nop 0
	global_load_lds_dwordx4 v192, s[50:51]
	s_add_u32 s30, s50, s4
	s_addc_u32 s31, s51, s5
	s_mov_b32 m0, s25
	s_nop 0
	global_load_lds_dwordx4 v192, s[30:31]
	s_barrier
	s_waitcnt lgkmcnt(0)
	s_waitcnt lgkmcnt(0)
	v_mfma_f32_16x16x32_bf16 v[92:95], v[162:165], v[200:203], v[92:95]
	v_mfma_f32_16x16x32_bf16 v[88:91], v[162:165], v[208:211], v[88:91]
	v_mfma_f32_16x16x32_bf16 v[84:87], v[170:173], v[200:203], v[84:87]
	v_mfma_f32_16x16x32_bf16 v[80:83], v[170:173], v[208:211], v[80:83]
	v_mfma_f32_16x16x32_bf16 v[76:79], v[178:181], v[200:203], v[76:79]
	v_mfma_f32_16x16x32_bf16 v[72:75], v[178:181], v[208:211], v[72:75]
	v_mfma_f32_16x16x32_bf16 v[68:71], v[186:189], v[200:203], v[68:71]
	v_mfma_f32_16x16x32_bf16 v[64:67], v[186:189], v[208:211], v[64:67]
	v_mfma_f32_16x16x32_bf16 v[92:95], v[166:169], v[204:207], v[92:95]
	v_mfma_f32_16x16x32_bf16 v[88:91], v[166:169], v[212:215], v[88:91]
	v_mfma_f32_16x16x32_bf16 v[84:87], v[174:177], v[204:207], v[84:87]
	v_mfma_f32_16x16x32_bf16 v[80:83], v[174:177], v[212:215], v[80:83]
	v_mfma_f32_16x16x32_bf16 v[76:79], v[182:185], v[204:207], v[76:79]
	v_mfma_f32_16x16x32_bf16 v[72:75], v[182:185], v[212:215], v[72:75]
	v_mfma_f32_16x16x32_bf16 v[68:71], v[196:199], v[204:207], v[68:71]
	v_mfma_f32_16x16x32_bf16 v[64:67], v[196:199], v[212:215], v[64:67]
	s_add_u32 s50, s55, 0x180
	s_addc_u32 s51, s72, 0
	s_mov_b32 m0, s26
	s_barrier
	ds_read_b128 v[162:165], v128 offset:49152
	ds_read_b128 v[166:169], v128 offset:50176
	ds_read_b128 v[170:173], v128 offset:51200
	ds_read_b128 v[174:177], v128 offset:52224
	ds_read_b128 v[178:181], v128 offset:53248
	ds_read_b128 v[182:185], v128 offset:54272
	ds_read_b128 v[186:189], v128 offset:55296
	ds_read_b128 v[196:199], v128 offset:56320
	global_load_lds_dwordx4 v192, s[50:51]
	s_add_u32 s30, s50, s4
	s_addc_u32 s31, s51, s5
	s_mov_b32 m0, s27
	s_nop 0
	global_load_lds_dwordx4 v192, s[30:31]
	s_barrier
	s_waitcnt lgkmcnt(0)
	s_waitcnt lgkmcnt(0)
	v_mfma_f32_16x16x32_bf16 v[60:63], v[162:165], v[146:149], v[60:63]
	v_mfma_f32_16x16x32_bf16 v[56:59], v[162:165], v[154:157], v[56:59]
	v_mfma_f32_16x16x32_bf16 v[52:55], v[170:173], v[146:149], v[52:55]
	v_mfma_f32_16x16x32_bf16 v[48:51], v[170:173], v[154:157], v[48:51]
	v_mfma_f32_16x16x32_bf16 v[44:47], v[178:181], v[146:149], v[44:47]
	v_mfma_f32_16x16x32_bf16 v[40:43], v[178:181], v[154:157], v[40:43]
	v_mfma_f32_16x16x32_bf16 v[36:39], v[186:189], v[146:149], v[36:39]
	v_mfma_f32_16x16x32_bf16 v[32:35], v[186:189], v[154:157], v[32:35]
	v_mfma_f32_16x16x32_bf16 v[60:63], v[166:169], v[150:153], v[60:63]
	v_mfma_f32_16x16x32_bf16 v[56:59], v[166:169], v[158:161], v[56:59]
	v_mfma_f32_16x16x32_bf16 v[52:55], v[174:177], v[150:153], v[52:55]
	v_mfma_f32_16x16x32_bf16 v[48:51], v[174:177], v[158:161], v[48:51]
	v_mfma_f32_16x16x32_bf16 v[44:47], v[182:185], v[150:153], v[44:47]
	v_mfma_f32_16x16x32_bf16 v[40:43], v[182:185], v[158:161], v[40:43]
	v_mfma_f32_16x16x32_bf16 v[36:39], v[196:199], v[150:153], v[36:39]
	v_mfma_f32_16x16x32_bf16 v[32:35], v[196:199], v[158:161], v[32:35]
	s_barrier
	s_add_u32 s50, s73, 0x180
	s_addc_u32 s51, s74, 0
	s_mov_b32 m0, s28
	s_nop 0
	global_load_lds_dwordx4 v192, s[50:51]
	s_add_u32 s30, s50, s4
	s_addc_u32 s31, s51, s5
	s_mov_b32 m0, s29
	s_nop 0
	global_load_lds_dwordx4 v192, s[30:31]
	s_waitcnt vmcnt(6)
	s_barrier
	v_mfma_f32_16x16x32_bf16 v[28:31], v[162:165], v[200:203], v[28:31]
	v_mfma_f32_16x16x32_bf16 v[24:27], v[162:165], v[208:211], v[24:27]
	v_mfma_f32_16x16x32_bf16 v[20:23], v[170:173], v[200:203], v[20:23]
	v_mfma_f32_16x16x32_bf16 v[16:19], v[170:173], v[208:211], v[16:19]
	v_mfma_f32_16x16x32_bf16 v[12:15], v[178:181], v[200:203], v[12:15]
	v_mfma_f32_16x16x32_bf16 v[8:11], v[178:181], v[208:211], v[8:11]
	v_mfma_f32_16x16x32_bf16 v[4:7], v[186:189], v[200:203], v[4:7]
	v_mfma_f32_16x16x32_bf16 v[0:3], v[186:189], v[208:211], v[0:3]
	v_mfma_f32_16x16x32_bf16 v[28:31], v[166:169], v[204:207], v[28:31]
	v_mfma_f32_16x16x32_bf16 v[24:27], v[166:169], v[212:215], v[24:27]
	v_mfma_f32_16x16x32_bf16 v[20:23], v[174:177], v[204:207], v[20:23]
	v_mfma_f32_16x16x32_bf16 v[16:19], v[174:177], v[212:215], v[16:19]
	v_mfma_f32_16x16x32_bf16 v[12:15], v[182:185], v[204:207], v[12:15]
	v_mfma_f32_16x16x32_bf16 v[8:11], v[182:185], v[212:215], v[8:11]
	v_mfma_f32_16x16x32_bf16 v[4:7], v[196:199], v[204:207], v[4:7]
	v_mfma_f32_16x16x32_bf16 v[0:3], v[196:199], v[212:215], v[0:3]
	s_add_i32 s48, s48, 2
	s_add_u32 s38, s38, 0x100
	s_addc_u32 s39, s39, 0
	s_cmp_lt_u32 s48, 12
	s_barrier
	s_cbranch_scc1 .LBB0_362
	v_add_u32_e32 v129, 0, v137
	s_add_u32 s0, s36, 0x780
	v_add_u32_e32 v142, 0x10000, v129
	s_addc_u32 s1, s37, 0
	ds_read_b128 v[130:133], v142
	ds_read_b128 v[134:137], v142 offset:1024
	ds_read_b128 v[138:141], v142 offset:2048
	ds_read_b128 v[146:149], v142 offset:3072
	ds_read_b128 v[150:153], v128
	ds_read_b128 v[154:157], v128 offset:1024
	ds_read_b128 v[158:161], v128 offset:2048
	ds_read_b128 v[162:165], v128 offset:3072
	ds_read_b128 v[166:169], v128 offset:4096
	ds_read_b128 v[170:173], v128 offset:5120
	ds_read_b128 v[174:177], v128 offset:6144
	ds_read_b128 v[178:181], v128 offset:7168
	v_lshl_add_u64 v[142:143], s[0:1], 0, v[192:193]
	v_readfirstlane_b32 s0, v144
	s_mov_b32 m0, s0
	v_readfirstlane_b32 s0, v145
	global_load_lds_dwordx4 v[142:143], off
	v_lshl_add_u64 v[142:143], v[142:143], 0, s[4:5]
	s_mov_b32 m0, s0
	s_nop 0
	global_load_lds_dwordx4 v[142:143], off
	s_barrier
	s_waitcnt lgkmcnt(0)
	s_waitcnt lgkmcnt(0)
	v_mfma_f32_16x16x32_bf16 v[124:127], v[150:153], v[130:133], v[124:127]
	v_mfma_f32_16x16x32_bf16 v[120:123], v[150:153], v[138:141], v[120:123]
	v_mfma_f32_16x16x32_bf16 v[116:119], v[158:161], v[130:133], v[116:119]
	v_mfma_f32_16x16x32_bf16 v[112:115], v[158:161], v[138:141], v[112:115]
	v_mfma_f32_16x16x32_bf16 v[108:111], v[166:169], v[130:133], v[108:111]
	v_mfma_f32_16x16x32_bf16 v[104:107], v[166:169], v[138:141], v[104:107]
	v_mfma_f32_16x16x32_bf16 v[100:103], v[174:177], v[130:133], v[100:103]
	v_mfma_f32_16x16x32_bf16 v[96:99], v[174:177], v[138:141], v[96:99]
	v_mfma_f32_16x16x32_bf16 v[124:127], v[154:157], v[134:137], v[124:127]
	v_mfma_f32_16x16x32_bf16 v[120:123], v[154:157], v[146:149], v[120:123]
	v_mfma_f32_16x16x32_bf16 v[116:119], v[162:165], v[134:137], v[116:119]
	v_mfma_f32_16x16x32_bf16 v[112:115], v[162:165], v[146:149], v[112:115]
	v_mfma_f32_16x16x32_bf16 v[108:111], v[170:173], v[134:137], v[108:111]
	v_mfma_f32_16x16x32_bf16 v[104:107], v[170:173], v[146:149], v[104:107]
	v_mfma_f32_16x16x32_bf16 v[100:103], v[178:181], v[134:137], v[100:103]
	v_mfma_f32_16x16x32_bf16 v[96:99], v[178:181], v[146:149], v[96:99]
	v_add_u32_e32 v190, 0x14000, v129
	s_barrier
	ds_read_b128 v[142:145], v190
	ds_read_b128 v[182:185], v190 offset:1024
	ds_read_b128 v[186:189], v190 offset:2048
	ds_read_b128 v[196:199], v190 offset:3072
	s_barrier
	s_waitcnt lgkmcnt(0)
	s_waitcnt lgkmcnt(0)
	v_mfma_f32_16x16x32_bf16 v[92:95], v[150:153], v[142:145], v[92:95]
	v_mfma_f32_16x16x32_bf16 v[88:91], v[150:153], v[186:189], v[88:91]
	v_mfma_f32_16x16x32_bf16 v[84:87], v[158:161], v[142:145], v[84:87]
	v_mfma_f32_16x16x32_bf16 v[80:83], v[158:161], v[186:189], v[80:83]
	v_mfma_f32_16x16x32_bf16 v[76:79], v[166:169], v[142:145], v[76:79]
	v_mfma_f32_16x16x32_bf16 v[72:75], v[166:169], v[186:189], v[72:75]
	v_mfma_f32_16x16x32_bf16 v[68:71], v[174:177], v[142:145], v[68:71]
	v_mfma_f32_16x16x32_bf16 v[64:67], v[174:177], v[186:189], v[64:67]
	v_mfma_f32_16x16x32_bf16 v[200:203], v[154:157], v[182:185], v[92:95]
	v_mfma_f32_16x16x32_bf16 v[150:153], v[154:157], v[196:199], v[88:91]
	v_mfma_f32_16x16x32_bf16 v[154:157], v[162:165], v[182:185], v[84:87]
	v_mfma_f32_16x16x32_bf16 v[158:161], v[162:165], v[196:199], v[80:83]
	v_mfma_f32_16x16x32_bf16 v[162:165], v[170:173], v[182:185], v[76:79]
	v_mfma_f32_16x16x32_bf16 v[166:169], v[170:173], v[196:199], v[72:75]
	v_mfma_f32_16x16x32_bf16 v[170:173], v[178:181], v[182:185], v[68:71]
	v_mfma_f32_16x16x32_bf16 v[174:177], v[178:181], v[196:199], v[64:67]
	s_barrier
	s_nop 0
	ds_read_b128 v[64:67], v128 offset:16384
	ds_read_b128 v[68:71], v128 offset:17408
	ds_read_b128 v[72:75], v128 offset:18432
	ds_read_b128 v[76:79], v128 offset:19456
	ds_read_b128 v[80:83], v128 offset:20480
	ds_read_b128 v[84:87], v128 offset:21504
	ds_read_b128 v[88:91], v128 offset:22528
	ds_read_b128 v[92:95], v128 offset:23552
	s_waitcnt vmcnt(4)
	s_barrier
	s_waitcnt lgkmcnt(0)
	s_waitcnt lgkmcnt(0)
	v_mfma_f32_16x16x32_bf16 v[60:63], v[64:67], v[130:133], v[60:63]
	v_mfma_f32_16x16x32_bf16 v[56:59], v[64:67], v[138:141], v[56:59]
	v_mfma_f32_16x16x32_bf16 v[52:55], v[72:75], v[130:133], v[52:55]
	v_mfma_f32_16x16x32_bf16 v[48:51], v[72:75], v[138:141], v[48:51]
	v_mfma_f32_16x16x32_bf16 v[44:47], v[80:83], v[130:133], v[44:47]
	v_mfma_f32_16x16x32_bf16 v[40:43], v[80:83], v[138:141], v[40:43]
	v_mfma_f32_16x16x32_bf16 v[36:39], v[88:91], v[130:133], v[36:39]
	v_mfma_f32_16x16x32_bf16 v[32:35], v[88:91], v[138:141], v[32:35]
	v_mfma_f32_16x16x32_bf16 v[60:63], v[68:71], v[134:137], v[60:63]
	v_mfma_f32_16x16x32_bf16 v[56:59], v[68:71], v[146:149], v[56:59]
	v_mfma_f32_16x16x32_bf16 v[52:55], v[76:79], v[134:137], v[52:55]
	v_mfma_f32_16x16x32_bf16 v[48:51], v[76:79], v[146:149], v[48:51]
	v_mfma_f32_16x16x32_bf16 v[44:47], v[84:87], v[134:137], v[44:47]
	v_mfma_f32_16x16x32_bf16 v[40:43], v[84:87], v[146:149], v[40:43]
	v_mfma_f32_16x16x32_bf16 v[36:39], v[92:95], v[134:137], v[36:39]
	v_mfma_f32_16x16x32_bf16 v[32:35], v[92:95], v[146:149], v[32:35]
	v_mfma_f32_16x16x32_bf16 v[28:31], v[64:67], v[142:145], v[28:31]
	v_mfma_f32_16x16x32_bf16 v[24:27], v[64:67], v[186:189], v[24:27]
	v_mfma_f32_16x16x32_bf16 v[20:23], v[72:75], v[142:145], v[20:23]
	v_mfma_f32_16x16x32_bf16 v[16:19], v[72:75], v[186:189], v[16:19]
	v_mfma_f32_16x16x32_bf16 v[12:15], v[80:83], v[142:145], v[12:15]
	v_mfma_f32_16x16x32_bf16 v[8:11], v[80:83], v[186:189], v[8:11]
	v_mfma_f32_16x16x32_bf16 v[4:7], v[88:91], v[142:145], v[4:7]
	v_mfma_f32_16x16x32_bf16 v[0:3], v[88:91], v[186:189], v[0:3]
	v_mfma_f32_16x16x32_bf16 v[130:133], v[68:71], v[182:185], v[28:31]
	v_mfma_f32_16x16x32_bf16 v[134:137], v[68:71], v[196:199], v[24:27]
	v_mfma_f32_16x16x32_bf16 v[138:141], v[76:79], v[182:185], v[20:23]
	v_mfma_f32_16x16x32_bf16 v[146:149], v[76:79], v[196:199], v[16:19]
	v_mfma_f32_16x16x32_bf16 v[178:181], v[84:87], v[182:185], v[12:15]
	v_mfma_f32_16x16x32_bf16 v[204:207], v[84:87], v[196:199], v[8:11]
	v_mfma_f32_16x16x32_bf16 v[142:145], v[92:95], v[182:185], v[4:7]
	v_mfma_f32_16x16x32_bf16 v[182:185], v[92:95], v[196:199], v[0:3]
	s_nop 1
	v_add_u32_e32 v0, 0x18000, v129
	s_barrier
	ds_read_b128 v[24:27], v0
	ds_read_b128 v[28:31], v0 offset:1024
	ds_read_b128 v[186:189], v0 offset:2048
	ds_read_b128 v[196:199], v0 offset:3072
	ds_read_b128 v[0:3], v128 offset:32768
	ds_read_b128 v[4:7], v128 offset:33792
	ds_read_b128 v[8:11], v128 offset:34816
	ds_read_b128 v[12:15], v128 offset:35840
	ds_read_b128 v[16:19], v128 offset:36864
	ds_read_b128 v[20:23], v128 offset:37888
	ds_read_b128 v[208:211], v128 offset:38912
	ds_read_b128 v[212:215], v128 offset:39936
	s_waitcnt vmcnt(2)
	s_barrier
	s_waitcnt lgkmcnt(0)
	s_waitcnt lgkmcnt(0)
	v_mfma_f32_16x16x32_bf16 v[64:67], v[0:3], v[24:27], v[124:127]
	v_mfma_f32_16x16x32_bf16 v[92:95], v[4:7], v[28:31], v[64:67]
	v_mfma_f32_16x16x32_bf16 v[64:67], v[0:3], v[186:189], v[120:123]
	v_mfma_f32_16x16x32_bf16 v[68:71], v[8:11], v[24:27], v[116:119]
	v_mfma_f32_16x16x32_bf16 v[72:75], v[8:11], v[186:189], v[112:115]
	v_mfma_f32_16x16x32_bf16 v[76:79], v[16:19], v[24:27], v[108:111]
	v_mfma_f32_16x16x32_bf16 v[80:83], v[16:19], v[186:189], v[104:107]
	v_mfma_f32_16x16x32_bf16 v[84:87], v[208:211], v[24:27], v[100:103]
	v_mfma_f32_16x16x32_bf16 v[88:91], v[208:211], v[186:189], v[96:99]
	v_mfma_f32_16x16x32_bf16 v[64:67], v[4:7], v[196:199], v[64:67]
	v_mfma_f32_16x16x32_bf16 v[68:71], v[12:15], v[28:31], v[68:71]
	v_mfma_f32_16x16x32_bf16 v[72:75], v[12:15], v[196:199], v[72:75]
	v_mfma_f32_16x16x32_bf16 v[76:79], v[20:23], v[28:31], v[76:79]
	v_mfma_f32_16x16x32_bf16 v[80:83], v[20:23], v[196:199], v[80:83]
	v_mfma_f32_16x16x32_bf16 v[84:87], v[212:215], v[28:31], v[84:87]
	v_mfma_f32_16x16x32_bf16 v[88:91], v[212:215], v[196:199], v[88:91]
	v_add_u32_e32 v96, 0x1c000, v129
	s_barrier
	ds_read_b128 v[216:219], v96
	ds_read_b128 v[220:223], v96 offset:1024
	ds_read_b128 v[224:227], v96 offset:2048
	ds_read_b128 v[228:231], v96 offset:3072
	s_waitcnt vmcnt(0)
	s_barrier
	s_waitcnt lgkmcnt(0)
	s_waitcnt lgkmcnt(0)
	v_mfma_f32_16x16x32_bf16 v[96:99], v[0:3], v[216:219], v[200:203]
	v_mfma_f32_16x16x32_bf16 v[0:3], v[0:3], v[224:227], v[150:153]
	v_mfma_f32_16x16x32_bf16 v[124:127], v[4:7], v[220:223], v[96:99]
	v_mfma_f32_16x16x32_bf16 v[96:99], v[4:7], v[228:231], v[0:3]
	v_mfma_f32_16x16x32_bf16 v[0:3], v[8:11], v[216:219], v[154:157]
	v_mfma_f32_16x16x32_bf16 v[100:103], v[12:15], v[220:223], v[0:3]
	v_mfma_f32_16x16x32_bf16 v[0:3], v[8:11], v[224:227], v[158:161]
	v_mfma_f32_16x16x32_bf16 v[104:107], v[12:15], v[228:231], v[0:3]
	v_mfma_f32_16x16x32_bf16 v[0:3], v[16:19], v[216:219], v[162:165]
	v_mfma_f32_16x16x32_bf16 v[108:111], v[20:23], v[220:223], v[0:3]
	v_mfma_f32_16x16x32_bf16 v[0:3], v[16:19], v[224:227], v[166:169]
	v_mfma_f32_16x16x32_bf16 v[112:115], v[20:23], v[228:231], v[0:3]
	v_mfma_f32_16x16x32_bf16 v[0:3], v[208:211], v[216:219], v[170:173]
	v_mfma_f32_16x16x32_bf16 v[116:119], v[212:215], v[220:223], v[0:3]
	v_mfma_f32_16x16x32_bf16 v[0:3], v[208:211], v[224:227], v[174:177]
	v_mfma_f32_16x16x32_bf16 v[120:123], v[212:215], v[228:231], v[0:3]
	s_barrier
	ds_read_b128 v[150:153], v128 offset:49152
	ds_read_b128 v[154:157], v128 offset:50176
	ds_read_b128 v[158:161], v128 offset:51200
	ds_read_b128 v[162:165], v128 offset:52224
	ds_read_b128 v[166:169], v128 offset:53248
	ds_read_b128 v[170:173], v128 offset:54272
	ds_read_b128 v[174:177], v128 offset:55296
	ds_read_b128 v[200:203], v128 offset:56320
	s_barrier
	s_waitcnt lgkmcnt(0)
	s_waitcnt lgkmcnt(0)
	v_mfma_f32_16x16x32_bf16 v[0:3], v[150:153], v[24:27], v[60:63]
	v_mfma_f32_16x16x32_bf16 v[8:11], v[158:161], v[24:27], v[52:55]
	v_mfma_f32_16x16x32_bf16 v[16:19], v[166:169], v[24:27], v[44:47]
	v_mfma_f32_16x16x32_bf16 v[24:27], v[174:177], v[24:27], v[36:39]
	v_mfma_f32_16x16x32_bf16 v[0:3], v[154:157], v[28:31], v[0:3]
	v_mfma_f32_16x16x32_bf16 v[4:7], v[150:153], v[186:189], v[56:59]
	v_mfma_f32_16x16x32_bf16 v[8:11], v[162:165], v[28:31], v[8:11]
	v_mfma_f32_16x16x32_bf16 v[12:15], v[158:161], v[186:189], v[48:51]
	v_mfma_f32_16x16x32_bf16 v[16:19], v[170:173], v[28:31], v[16:19]
	v_mfma_f32_16x16x32_bf16 v[20:23], v[166:169], v[186:189], v[40:43]
	v_mfma_f32_16x16x32_bf16 v[24:27], v[200:203], v[28:31], v[24:27]
	v_mfma_f32_16x16x32_bf16 v[28:31], v[174:177], v[186:189], v[32:35]
	v_mfma_f32_16x16x32_bf16 v[4:7], v[154:157], v[196:199], v[4:7]
	v_mfma_f32_16x16x32_bf16 v[12:15], v[162:165], v[196:199], v[12:15]
	v_mfma_f32_16x16x32_bf16 v[20:23], v[170:173], v[196:199], v[20:23]
	v_mfma_f32_16x16x32_bf16 v[28:31], v[200:203], v[196:199], v[28:31]
	v_mfma_f32_16x16x32_bf16 v[32:35], v[150:153], v[216:219], v[130:133]
	v_mfma_f32_16x16x32_bf16 v[36:39], v[150:153], v[224:227], v[134:137]
	v_mfma_f32_16x16x32_bf16 v[40:43], v[158:161], v[216:219], v[138:141]
	v_mfma_f32_16x16x32_bf16 v[44:47], v[158:161], v[224:227], v[146:149]
	v_mfma_f32_16x16x32_bf16 v[48:51], v[166:169], v[216:219], v[178:181]
	v_mfma_f32_16x16x32_bf16 v[52:55], v[166:169], v[224:227], v[204:207]
	v_mfma_f32_16x16x32_bf16 v[56:59], v[174:177], v[216:219], v[142:145]
	v_mfma_f32_16x16x32_bf16 v[60:63], v[174:177], v[224:227], v[182:185]
	v_mfma_f32_16x16x32_bf16 v[32:35], v[154:157], v[220:223], v[32:35]
	v_mfma_f32_16x16x32_bf16 v[36:39], v[154:157], v[228:231], v[36:39]
	v_mfma_f32_16x16x32_bf16 v[40:43], v[162:165], v[220:223], v[40:43]
	v_mfma_f32_16x16x32_bf16 v[44:47], v[162:165], v[228:231], v[44:47]
	v_mfma_f32_16x16x32_bf16 v[48:51], v[170:173], v[220:223], v[48:51]
	v_mfma_f32_16x16x32_bf16 v[52:55], v[170:173], v[228:231], v[52:55]
	v_mfma_f32_16x16x32_bf16 v[56:59], v[200:203], v[220:223], v[56:59]
	v_mfma_f32_16x16x32_bf16 v[60:63], v[200:203], v[228:231], v[60:63]
	s_cmpk_gt_u32 s47, 0xff
	s_barrier
	s_cbranch_scc1 .LBB0_365
	s_barrier
